# attention unit set-up: key-bias copy waits behind the first K/V DMA and Q loads (one round trip instead of two)
# baseline (speedup 1.0000x reference)
;   #define DMA_K(t,slot) glds16(ksrc+(long)(t)*KVBLK*KP,(unsigned)__builtin_amdgcn_readfirstlane(kdst+(slot)))
;   #define DMA_V(t,slot) glds16(vsrc+(long)(t)*KVBLK*KP,(unsigned)__builtin_amdgcn_readfirstlane(vdst+(slot)))
; template<int THRL> __device__ __forceinline__ void attn_unit(int b,int h,int qb,const bf16*Q,const bf16*__restrict__ K,const bf16*__restrict__ V,bf16*O,const float*__restrict__ CK,const float*__restrict__ KMX,const float*__restrict__ QSV,char*shm){
;     ...
;   const int NT=(q0+QB)/KVBLK-ts;
;   { float*ckw=(float*)(shm+LDS_CK); const int nk4=NT*(KVBLK/4);
;     for(int i=tid;i<nk4;i+=NW*64){ const f32x4v c4=*reinterpret_cast<const f32x4v*>(CK+4*i); *reinterpret_cast<f32x4v*>(ckw+4*i)=c4; } }
;   const lds_fptr ckl=(lds_fptr)(shm3f+LDS_CK)+4*hi;
;     ...
;   DMA_K(0,0);DMA_V(0,0);DMA_K(1,SLOTB);
;   bf16x8 qr[4];
;   #pragma unroll
;   for(int d0=0;d0<4;++d0)qr[d0]=*reinterpret_cast<const bf16x8*>(&Qw[(long)r32*QP+d0*16+hi*8]);
;     ...
;   DMA_K(2,2*SLOTB);
.LBB0_716:
	s_add_i32 s4, s72, -4
	s_min_i32 s74, s16, s4
	s_and_b32 s6, s74, -2
	s_sub_i32 s64, s72, s6
	s_lshl_b32 s7, s64, 4
	v_cmp_gt_i32_e32 vcc, s7, v116
	s_and_saveexec_b64 s[4:5], vcc
	s_cbranch_execz .LBB0_719
	s_lshl_b32 s16, s6, 6
	s_ashr_i32 s17, s16, 31
	s_lshl_b64 s[16:17], s[16:17], 2
	s_add_u32 s14, s14, s16
	s_addc_u32 s15, s15, s17
	v_lshlrev_b32_e32 v0, 4, v116
	global_load_dwordx4 v[4:7], v0, s[14:15]
	v_add_u32_e32 v3, 0x200, v116
	v_cmp_gt_i32_e32 vcc, s7, v3
	v_add_u32_e32 v1, 0x2000, v0
	s_and_b64 exec, exec, vcc
	s_cbranch_execz .Lck_ld_done
	global_load_dwordx4 v[8:11], v1, s[14:15]
	v_add_u32_e32 v3, 0x400, v116
	v_cmp_gt_i32_e32 vcc, s7, v3
	v_add_u32_e32 v1, 0x4000, v0
	s_and_b64 exec, exec, vcc
	s_cbranch_execz .Lck_ld_done
	global_load_dwordx4 v[12:15], v1, s[14:15]
	v_add_u32_e32 v3, 0x600, v116
	v_cmp_gt_i32_e32 vcc, s7, v3
	v_add_u32_e32 v1, 0x6000, v0
	s_and_b64 exec, exec, vcc
	s_cbranch_execz .Lck_ld_done
	global_load_dwordx4 v[16:19], v1, s[14:15]
.Lck_ld_done:
.LBB0_719:
	s_or_b64 exec, exec, s[4:5]
	s_lshr_b32 s4, s13, 29
	s_add_i32 s4, s12, s4
	s_ashr_i32 s18, s4, 3
	s_and_b32 s4, s4, 0x3fffff8
	s_ashr_i32 s19, s18, 31
	s_sub_i32 s7, s12, s4
	s_ashr_i32 s13, s70, 6
	s_lshl_b64 s[4:5], s[18:19], 13
	s_ashr_i32 s14, s2, 31
	s_add_u32 s4, s4, s2
	s_addc_u32 s5, s5, s14
	s_lshl_b32 s2, s13, 5
	s_ashr_i32 s14, s2, 31
	s_add_u32 s4, s4, s2
	s_addc_u32 s5, s5, s14
	s_lshl_b64 s[4:5], s[4:5], 11
	s_add_u32 s14, s29, s4
	s_addc_u32 s15, s30, s5
	s_lshl_b32 s4, s7, 6
	s_ashr_i32 s5, s4, 31
	s_lshl_b64 s[16:17], s[4:5], 1
	s_add_u32 s14, s14, s16
	s_addc_u32 s15, s15, s17
	s_ashr_i32 s7, s6, 31
	s_lshl_b64 s[4:5], s[6:7], 15
	s_lshl_b64 s[20:21], s[18:19], 22
	s_add_u32 s4, s4, s20
	s_addc_u32 s5, s5, s21
	s_lshl_b64 s[4:5], s[4:5], 1
	s_add_u32 s20, s31, s4
	s_addc_u32 s21, s34, s5
	s_add_u32 s20, s20, s16
	s_addc_u32 s21, s21, s17
	s_add_u32 s4, s35, s4
	s_addc_u32 s5, s36, s5
	s_add_u32 s4, s4, s16
	v_lshlrev_b32_e32 v192, 10, v218
	s_addc_u32 s5, s5, s17
	v_lshl_add_u64 v[0:1], s[20:21], 0, v[192:193]
	s_lshl_b32 s20, s13, 3
	s_ashr_i32 s21, s20, 31
	s_lshl_b32 s22, s13, 4
	v_lshrrev_b32_e32 v190, 2, v218
	v_lshl_add_u64 v[112:113], s[20:21], 1, v[0:1]
	v_and_or_b32 v0, s22, 48, v190
	v_lshlrev_b32_e32 v0, 10, v0
	v_mov_b32_e32 v1, v193
	v_lshl_add_u64 v[0:1], s[4:5], 0, v[0:1]
	s_ashr_i32 s4, s70, 3
	s_and_b32 s22, s4, 0xffffffe0
	v_lshlrev_b32_e32 v219, 3, v116
	s_ashr_i32 s23, s22, 31
	v_and_b32_e32 v223, 24, v219
	s_lshl_b32 s66, s13, 10
	v_lshl_add_u64 v[0:1], s[22:23], 1, v[0:1]
	v_lshlrev_b32_e32 v2, 1, v223
	v_mov_b32_e32 v3, v193
	s_add_i32 s65, s66, s48
	s_mov_b32 s4, m0
	s_mov_b32 m0, s65
	s_nop 0
	global_load_lds_dwordx4 v[112:113], off
	s_mov_b32 m0, s4
	v_lshl_add_u64 v[114:115], v[0:1], 0, v[2:3]
	s_add_i32 s66, s66, s49
	s_mov_b32 s4, m0
	s_mov_b32 m0, s66
	s_nop 0
	global_load_lds_dwordx4 v[114:115], off
	s_mov_b32 m0, s4
	v_lshrrev_b32_e32 v221, 5, v218
	s_mov_b64 s[4:5], 0x10000
	v_and_b32_e32 v220, 31, v116
	v_lshl_add_u64 v[0:1], v[112:113], 0, s[4:5]
	v_lshlrev_b32_e32 v24, 4, v221
	s_add_i32 s4, s65, 0x2000
	s_mov_b32 s5, m0
	s_mov_b32 m0, s4
	s_nop 0
	global_load_lds_dwordx4 v[0:1], off
	s_mov_b32 m0, s5
	v_lshl_or_b32 v0, v220, 11, v24
	v_mov_b32_e32 v1, v193
	v_lshl_add_u64 v[0:1], s[14:15], 0, v[0:1]
	flat_load_dwordx4 v[108:111], v[0:1]
	flat_load_dwordx4 v[104:107], v[0:1] offset:32
	flat_load_dwordx4 v[100:103], v[0:1] offset:64
	flat_load_dwordx4 v[96:99], v[0:1] offset:96
	v_lshlrev_b32_e32 v0, 10, v221
	v_lshlrev_b32_e32 v1, 4, v220
	v_add3_u32 v230, s28, v0, v1
	s_add_i32 s4, s65, 0x4000
	v_lshl_add_u64 v[0:1], v[112:113], 0, s[46:47]
	s_mov_b32 s5, m0
	s_mov_b32 m0, s4
	s_nop 0
	global_load_lds_dwordx4 v[0:1], off
	s_mov_b32 m0, s5
	s_lshl_b32 s4, s64, 4
	v_lshl_add_u32 v20, v116, 4, s50
	v_cmp_gt_i32_e32 vcc, s4, v116
	s_and_b64 exec, exec, vcc
	s_cbranch_execz .Lck_wr_done
	s_waitcnt vmcnt(8)
	ds_write_b128 v20, v[4:7]
	v_add_u32_e32 v21, 0x200, v116
	v_cmp_gt_i32_e32 vcc, s4, v21
	s_and_b64 exec, exec, vcc
	s_cbranch_execz .Lck_wr_done
	ds_write_b128 v20, v[8:11] offset:8192
	v_add_u32_e32 v21, 0x400, v116
	v_cmp_gt_i32_e32 vcc, s4, v21
	s_and_b64 exec, exec, vcc
	s_cbranch_execz .Lck_wr_done
	ds_write_b128 v20, v[12:15] offset:16384
	v_add_u32_e32 v21, 0x600, v116
	v_cmp_gt_i32_e32 vcc, s4, v21
	s_and_b64 exec, exec, vcc
	s_cbranch_execz .Lck_wr_done
	ds_write_b128 v20, v[16:19] offset:24576
; __device__ __forceinline__ void cmask(f32x16&p0,f32x16&p1,int jb,int qrel,int hi){
;   const float NEG=-INFINITY; int kb=64*jb+4*hi;
;   #pragma unroll
;   for(int r=0;r<16;++r){int kv=kb+(r&3)+8*(r>>2); if(kv>qrel)p0[r]=NEG; if(kv+32>qrel)p1[r]=NEG;}
; }
; __device__ __forceinline__ void glds16(const void*gsrc,unsigned lds_dst){unsigned keep;
;   asm volatile("s_mov_b32 %0, m0\n\ts_mov_b32 m0, %2\n\ts_nop 0\n\tglobal_load_lds_dwordx4 %1, off\n\ts_mov_b32 m0, %0":"=&s"(keep):"v"(gsrc),"s"(lds_dst):"memory");}
; __device__ __forceinline__ float max3f(float a,float b,float c){float r;asm("v_max3_f32 %0, %1, %2, %3":"=v"(r):"v"(a),"v"(b),"v"(c));return r;}
; __device__ __forceinline__ float max2f(float a,float b){float r;asm("v_max_f32_e32 %0, %1, %2":"=v"(r):"v"(a),"v"(b));return r;}
; __device__ __forceinline__ float fadd_s(float a,float b){float r;asm("v_add_f32_e32 %0, %1, %2":"=v"(r):"v"(a),"v"(b));return r;}
; __device__ __forceinline__ float fsub_s(float a,float b){float r;asm("v_sub_f32_e32 %0, %1, %2":"=v"(r):"v"(a),"v"(b));return r;}
; __device__ __forceinline__ unsigned cvtpk_s(float lo,float hi){f32x2_t v={lo,hi};bf16x2_t b=__builtin_convertvector(v,bf16x2_t);return __builtin_bit_cast(unsigned,b);}
; __device__ __forceinline__ void qkt(f32x16&p0,f32x16&p1,const char*Kslot,const bf16x8*qr,const f32x16&negm,int r32,int hi){
; template<int THRL> __device__ __forceinline__ void attn_unit(int b,int h,int qb,const bf16*Q,const bf16*__restrict__ K,const bf16*__restrict__ V,bf16*O,const float*__restrict__ CK,const float*__restrict__ KMX,const float*__restrict__ QSV,char*shm){
;     ...
;     for(int i=tid;i<nk4;i+=NW*64){ const f32x4v c4=*reinterpret_cast<const f32x4v*>(CK+4*i); *reinterpret_cast<f32x4v*>(ckw+4*i)=c4; } }
;   const lds_fptr ckl=(lds_fptr)(shm3f+LDS_CK)+4*hi;
;     ...
;   DMA_K(0,0);DMA_V(0,0);DMA_K(1,SLOTB);
;   bf16x8 qr[4];
;   #pragma unroll
;   for(int d0=0;d0<4;++d0)qr[d0]=*reinterpret_cast<const bf16x8*>(&Qw[(long)r32*QP+d0*16+hi*8]);
;   float mhat=0.f,l_reg=0.f;f32x16 o[2];o[0]=f32x16{};o[1]=f32x16{};const f32x16 zero16=f32x16{};
;   const int qrel=wid*QBLK+r32;
;     ...
;   bool resc=false;
;     ...
;   f32x16 pA0,pA1,pB0,pB1;
;   int sl_prev=0,sl_cur=0,sl_next=SLOTB;
;     ...
;   DMA_K(2,2*SLOTB);
;   WAIT_BAR(3);
;   qkt(pA0,pA1,Kbase,qr,zero16,r32,hi);asm volatile("s_nop 15\n\ts_nop 7":"+v"(pA0),"+v"(pA1));KBIAS(pA0,pA1,0);CMASK(pA0,pA1,0);
.Lck_wr_done:
	s_mov_b64 exec, -1
	s_waitcnt vmcnt(3) lgkmcnt(0)
	s_barrier
	ds_read_b128 v[0:3], v230
	ds_read_b128 v[16:19], v230 offset:512
	v_add_u32_e32 v224, s50, v24
	s_cmp_lt_i32 s64, 5
	v_lshlrev_b32_e32 v222, 2, v221
	v_or_b32_e32 v229, s2, v220
	s_waitcnt vmcnt(0) lgkmcnt(0)
	v_mfma_f32_32x32x16_bf16 v[0:15], v[0:3], v[108:111], 0
	v_mfma_f32_32x32x16_bf16 v[30:45], v[16:19], v[108:111], 0
	ds_read_b128 v[16:19], v230 offset:2048
	ds_read_b128 v[20:23], v230 offset:2560
	s_waitcnt lgkmcnt(1)
	v_mfma_f32_32x32x16_bf16 v[0:15], v[16:19], v[104:107], v[0:15]
	s_waitcnt lgkmcnt(0)
	v_mfma_f32_32x32x16_bf16 v[30:45], v[20:23], v[104:107], v[30:45]
	ds_read_b128 v[16:19], v230 offset:4096
	ds_read_b128 v[20:23], v230 offset:4608
	s_waitcnt lgkmcnt(1)
	v_mfma_f32_32x32x16_bf16 v[0:15], v[16:19], v[100:103], v[0:15]
	s_waitcnt lgkmcnt(0)
	v_mfma_f32_32x32x16_bf16 v[30:45], v[20:23], v[100:103], v[30:45]
	ds_read_b128 v[16:19], v230 offset:6144
	ds_read_b128 v[20:23], v230 offset:6656
	s_waitcnt lgkmcnt(1)
	v_mfma_f32_32x32x16_bf16 v[0:15], v[16:19], v[96:99], v[0:15]
	s_waitcnt lgkmcnt(0)
	v_mfma_f32_32x32x16_bf16 v[30:45], v[20:23], v[96:99], v[30:45]
	s_nop 15
	s_nop 7
	ds_read_b128 v[16:19], v224 offset:96
	ds_read_b128 v[20:23], v224 offset:64
	ds_read_b128 v[24:27], v224
	ds_read_b128 v[46:49], v224 offset:32
	s_waitcnt lgkmcnt(3)
	s_nop 4
	v_sub_f32_e32 v15, v15, v19
	v_sub_f32_e32 v14, v14, v18
	s_waitcnt lgkmcnt(2)
	v_sub_f32_e32 v11, v11, v23
	v_sub_f32_e32 v10, v10, v22
	v_sub_f32_e32 v9, v9, v21
	v_sub_f32_e32 v8, v8, v20
	s_waitcnt lgkmcnt(0)
	v_sub_f32_e32 v7, v7, v49
	v_sub_f32_e32 v6, v6, v48
	v_sub_f32_e32 v5, v5, v47
	v_sub_f32_e32 v4, v4, v46
	v_sub_f32_e32 v3, v3, v27
	v_sub_f32_e32 v2, v2, v26
	v_sub_f32_e32 v1, v1, v25
	v_sub_f32_e32 v0, v0, v24
	ds_read_b128 v[18:21], v224 offset:224
	ds_read_b128 v[22:25], v224 offset:192
	ds_read_b128 v[46:49], v224 offset:128
	ds_read_b128 v[26:29], v224 offset:160
	v_sub_f32_e32 v13, v13, v17
	v_sub_f32_e32 v12, v12, v16
	s_waitcnt lgkmcnt(3)
	v_sub_f32_e32 v17, v45, v21
	v_sub_f32_e32 v16, v44, v20
	v_sub_f32_e32 v19, v43, v19
	v_sub_f32_e32 v18, v42, v18
	s_waitcnt lgkmcnt(2)
	v_sub_f32_e32 v21, v41, v25
	v_sub_f32_e32 v20, v40, v24
	v_sub_f32_e32 v23, v39, v23
	v_sub_f32_e32 v22, v38, v22
	s_waitcnt lgkmcnt(0)
	v_sub_f32_e32 v25, v37, v29
	v_sub_f32_e32 v24, v36, v28
	v_sub_f32_e32 v27, v35, v27
	v_sub_f32_e32 v26, v34, v26
	v_sub_f32_e32 v29, v33, v49
	v_sub_f32_e32 v28, v32, v48
	v_sub_f32_e32 v31, v31, v47
	v_sub_f32_e32 v30, v30, v46
	s_cbranch_scc0 .LBB0_721
	s_lshl_b32 s2, s64, 6
	v_subrev_u32_e32 v32, s2, v222
	v_add_u32_e32 v34, 0x120, v32
	v_add_u32_e32 v33, 0x100, v32
	v_cmp_le_i32_e64 s[4:5], v34, v229
	v_cmp_le_i32_e32 vcc, v33, v229
	s_nop 0
	v_cndmask_b32_e64 v30, v217, v30, s[4:5]
	v_cmp_lt_i32_e64 s[4:5], v33, v229
	v_add_u32_e32 v33, 0x121, v32
	v_cndmask_b32_e32 v0, v217, v0, vcc
	v_cmp_le_i32_e32 vcc, v33, v229
	v_add_u32_e32 v33, 0x102, v32
	v_cndmask_b32_e64 v1, v217, v1, s[4:5]
	v_cndmask_b32_e32 v31, v217, v31, vcc
	v_cmp_le_i32_e32 vcc, v33, v229
	v_add_u32_e32 v33, 0x122, v32
	s_nop 0
	v_cndmask_b32_e32 v2, v217, v2, vcc
	v_cmp_le_i32_e32 vcc, v33, v229
	v_add_u32_e32 v33, 0x103, v32
	s_nop 0
	v_cndmask_b32_e32 v28, v217, v28, vcc
	v_cmp_le_i32_e32 vcc, v33, v229
	v_add_u32_e32 v33, 0x123, v32
	s_nop 0
	v_cndmask_b32_e32 v3, v217, v3, vcc
	v_cmp_le_i32_e32 vcc, v33, v229
	v_add_u32_e32 v33, 0x108, v32
	s_nop 0
	v_cndmask_b32_e32 v29, v217, v29, vcc
	v_cmp_le_i32_e32 vcc, v33, v229
	v_add_u32_e32 v33, 0x128, v32
	s_nop 0
	v_cndmask_b32_e32 v4, v217, v4, vcc
	v_cmp_le_i32_e32 vcc, v33, v229
	v_add_u32_e32 v33, 0x109, v32
	s_nop 0
	v_cndmask_b32_e32 v26, v217, v26, vcc
	v_cmp_le_i32_e32 vcc, v33, v229
	v_add_u32_e32 v33, 0x129, v32
	s_nop 0
	v_cndmask_b32_e32 v5, v217, v5, vcc
	v_cmp_le_i32_e32 vcc, v33, v229
	v_add_u32_e32 v33, 0x10a, v32
	s_nop 0
	v_cndmask_b32_e32 v27, v217, v27, vcc
	v_cmp_le_i32_e32 vcc, v33, v229
	v_add_u32_e32 v33, 0x12a, v32
	s_nop 0
	v_cndmask_b32_e32 v6, v217, v6, vcc
	v_cmp_le_i32_e32 vcc, v33, v229
	v_add_u32_e32 v33, 0x10b, v32
	s_nop 0
	v_cndmask_b32_e32 v24, v217, v24, vcc
	v_cmp_le_i32_e32 vcc, v33, v229
	v_add_u32_e32 v33, 0x12b, v32
	s_nop 0
	v_cndmask_b32_e32 v7, v217, v7, vcc
	v_cmp_le_i32_e32 vcc, v33, v229
	v_add_u32_e32 v33, 0x110, v32
	s_nop 0
	v_cndmask_b32_e32 v25, v217, v25, vcc
	v_cmp_le_i32_e32 vcc, v33, v229
	v_add_u32_e32 v33, 0x130, v32
	s_nop 0
	v_cndmask_b32_e32 v8, v217, v8, vcc
	v_cmp_le_i32_e32 vcc, v33, v229
	v_add_u32_e32 v33, 0x111, v32
	s_nop 0
	v_cndmask_b32_e32 v22, v217, v22, vcc
	v_cmp_le_i32_e32 vcc, v33, v229
	v_add_u32_e32 v33, 0x131, v32
	s_nop 0
	v_cndmask_b32_e32 v9, v217, v9, vcc
	v_cmp_le_i32_e32 vcc, v33, v229
	v_add_u32_e32 v33, 0x112, v32
	s_nop 0
	v_cndmask_b32_e32 v23, v217, v23, vcc
	v_cmp_le_i32_e32 vcc, v33, v229
	v_add_u32_e32 v33, 0x132, v32
	s_nop 0
	v_cndmask_b32_e32 v10, v217, v10, vcc
	v_cmp_le_i32_e32 vcc, v33, v229
	v_add_u32_e32 v33, 0x113, v32
	s_nop 0
	v_cndmask_b32_e32 v20, v217, v20, vcc
	v_cmp_le_i32_e32 vcc, v33, v229
	v_add_u32_e32 v33, 0x133, v32
	s_nop 0
	v_cndmask_b32_e32 v11, v217, v11, vcc
	v_cmp_le_i32_e32 vcc, v33, v229
	v_add_u32_e32 v33, 0x118, v32
	s_nop 0
	v_cndmask_b32_e32 v21, v217, v21, vcc
	v_cmp_le_i32_e32 vcc, v33, v229
	v_add_u32_e32 v33, 0x138, v32
	s_nop 0
	v_cndmask_b32_e32 v12, v217, v12, vcc
	v_cmp_le_i32_e32 vcc, v33, v229
	v_add_u32_e32 v33, 0x119, v32
	s_nop 0
	v_cndmask_b32_e32 v18, v217, v18, vcc
	v_cmp_le_i32_e32 vcc, v33, v229
	v_add_u32_e32 v33, 0x139, v32
	s_nop 0
	v_cndmask_b32_e32 v13, v217, v13, vcc
	v_cmp_le_i32_e32 vcc, v33, v229
	v_add_u32_e32 v33, 0x11a, v32
	s_nop 0
	v_cndmask_b32_e32 v19, v217, v19, vcc
	v_cmp_le_i32_e32 vcc, v33, v229
	v_add_u32_e32 v33, 0x13a, v32
	s_nop 0
	v_cndmask_b32_e32 v14, v217, v14, vcc
	v_cmp_le_i32_e32 vcc, v33, v229
	v_add_u32_e32 v33, 0x11b, v32
	v_add_u32_e32 v32, 0x13b, v32
	v_cndmask_b32_e32 v16, v217, v16, vcc
	v_cmp_le_i32_e32 vcc, v33, v229
	s_nop 1
	v_cndmask_b32_e32 v15, v217, v15, vcc
	v_cmp_le_i32_e32 vcc, v32, v229
	s_nop 1
	v_cndmask_b32_e32 v17, v217, v17, vcc
